# v33 + strategy 4: one static s_setprio 1 for waves 4-7 across the attention stream (reset before the mLSTM output units)
# speedup vs baseline: 1.0002x; 1.0002x over previous
; template <int L, int K>
; __device__ __forceinline__ void phase_body(char* lds, int rep_) {
;     ...
;                 for (;;) {
;                     volatile int* slot = (volatile int*)(lds + LDS_MISC);
;                     if (tid == 0) *slot = fox::fox_take(qh, xcc);
;                     __syncthreads();
;                     const int ci = __builtin_amdgcn_readfirstlane(*slot);
;                     __syncthreads();
;                     if (ci < 0) break;
;                     fox::Seam S;
;                     fox::BlockRef cur, nxt; fox::fox_ref(ci, cur, PROJ, MIX); cur.jlo = fox::fox_jlo(CF, nrm, cur.head, cur.P0);
;                     fox::fox_prime(cur, lds, S);
;                     for (;;) {
;                         const bool more = fox::fox_block(cur, nxt, qh, nrm, PROJ, MIX, lds, S, CF, fnorm);
;                         if (!more) break;
;                         cur = nxt;
;                     }
.LBB0_678:
.LBB0_679:
	v_readfirstlane_b32 s98, v194
	s_nop 3
	s_lshr_b32 s98, s98, 8
	s_cmp_eq_u32 s98, 0
	s_cbranch_scc1 .Lprio_skip_1
	s_setprio 1

; #define DEP_() ((unsigned*)(load_params().ws + WS_CTL) + 128 + L * 64 + rp_ * 32)
; __device__ __forceinline__ int fetch_item(unsigned* ctr, char* lds) {
;     volatile int* slot = (volatile int*)(lds + LDS_MISC);
;     if (threadIdx.x == 0) *slot = (int)atomicAdd(ctr, 1u);
;     __syncthreads();
;     const int v = __builtin_amdgcn_readfirstlane(*slot);
; template <int L, int K>
; __device__ __forceinline__ void phase_body(char* lds, int rep_) {
;     ...
;         wait_count(DEP_() + 3, 32u);
;         for (;;) { const int u = fetch_item(DEP_() + 4, lds); if (u >= 4 * NCH) break; const Params P = load_params(); mlstm_out_unit(P, L, u & 3, u >> 2, lds); }
.LBB0_972:
	s_setprio 0
	s_mov_b64 s[8:9], s[0:1]
	s_and_saveexec_b64 s[6:7], s[4:5]
	s_cbranch_execz .LBB0_974
	s_load_dwordx2 s[8:9], s[8:9], 0x90
	s_mov_b64 s[10:11], src_shared_base
	s_cmp_lg_u32 s24, -1
	s_waitcnt lgkmcnt(0)
	v_mov_b64_e32 v[2:3], s[8:9]
	flat_atomic_add v4, v[2:3], v1 offset:528 sc0
	s_cselect_b32 s8, s24, 0
	s_cselect_b32 s9, s11, 0
	v_mov_b32_e32 v2, s8
	v_mov_b32_e32 v3, s9
	s_waitcnt vmcnt(0) lgkmcnt(0)
	flat_store_dword v[2:3], v4 sc0 sc1
	s_waitcnt vmcnt(0)

; #define DEP_() ((unsigned*)(load_params().ws + WS_CTL) + 128 + L * 64 + rp_ * 32)
; __device__ __forceinline__ int fetch_item(unsigned* ctr, char* lds) {
;     volatile int* slot = (volatile int*)(lds + LDS_MISC);
;     if (threadIdx.x == 0) *slot = (int)atomicAdd(ctr, 1u);
;     __syncthreads();
;     const int v = __builtin_amdgcn_readfirstlane(*slot);
; template <int L, int K>
; __device__ __forceinline__ void phase_body(char* lds, int rep_) {
;     ...
;         wait_count(DEP_() + 3, 32u);
;         for (;;) { const int u = fetch_item(DEP_() + 4, lds); if (u >= 4 * NCH) break; const Params P = load_params(); mlstm_out_unit(P, L, u & 3, u >> 2, lds); }
.LBB0_2400:
	s_setprio 0
	s_mov_b64 s[8:9], s[0:1]
	s_and_saveexec_b64 s[6:7], s[4:5]
	s_cbranch_execz .LBB0_2402
	s_load_dwordx2 s[8:9], s[8:9], 0x90
	s_mov_b64 s[10:11], src_shared_base
	s_cmp_lg_u32 s24, -1
	s_waitcnt lgkmcnt(0)
	v_mov_b64_e32 v[2:3], s[8:9]
	flat_atomic_add v4, v[2:3], v1 offset:784 sc0
	s_cselect_b32 s8, s24, 0
	s_cselect_b32 s9, s11, 0
	v_mov_b32_e32 v2, s8
	v_mov_b32_e32 v3, s9
	s_waitcnt vmcnt(0) lgkmcnt(0)
	flat_store_dword v[2:3], v4 sc0 sc1
	s_waitcnt vmcnt(0)
